# dilated attention epilogue: state and y stores widened to 16 bytes per lane via permlane32 swap (4 stores instead of 8)
# speedup vs baseline: 1.0891x; 1.0330x over previous
.LBB0_1686:
	s_lshr_b32 s14, s40, 2
	s_and_b64 s[12:13], s[26:27], exec
	s_cselect_b32 s14, s14, s40
	s_and_b64 s[12:13], s[28:29], exec
	s_cselect_b32 s16, 0, s14
	s_and_b32 s12, s40, 3
	s_add_i32 s14, s40, s38
	s_or_b32 s15, s12, s37
	s_and_b64 s[12:13], s[26:27], exec
	s_cselect_b32 s15, s15, s36
	s_and_b64 s[12:13], s[28:29], exec
	s_cselect_b32 s15, s14, s15
	s_lshl_b32 s14, s15, 8
	s_add_i32 s42, s14, s9
	v_or_b32_e32 v120, s42, v122
	v_ashrrev_i32_e32 v121, 31, v120
	v_lshlrev_b64 v[2:3], s41, v[120:121]
	v_lshl_add_u64 v[116:117], v[2:3], 0, s[16:17]
	s_barrier
	v_lshlrev_b64 v[114:115], 11, v[116:117]
	v_lshl_add_u64 v[118:119], v[110:111], 0, v[114:115]
	s_cmp_eq_u32 s40, 0
	s_cbranch_scc1 .Lw0_L1
	s_and_b64 vcc, exec, s[24:25]
	s_cbranch_vccnz .Lw9_L1
	s_waitcnt vmcnt(4)
	s_branch .Lwd_L1
.Lw9_L1:
	s_waitcnt vmcnt(5)
	s_branch .Lwd_L1

.LBB0_1732:
	v_cvt_pk_bf16_f32 v48, v32, v33
	v_cvt_pk_bf16_f32 v49, v34, v35
	v_cvt_pk_bf16_f32 v50, v36, v37
	v_cvt_pk_bf16_f32 v51, v38, v39
	v_cvt_pk_bf16_f32 v52, v40, v41
	v_cvt_pk_bf16_f32 v53, v42, v43
	v_cvt_pk_bf16_f32 v54, v44, v45
	v_cvt_pk_bf16_f32 v55, v46, v47
	s_nop 3
	v_cvt_pk_bf16_f32 v56, v16, v17
	v_cvt_pk_bf16_f32 v57, v18, v19
	v_cvt_pk_bf16_f32 v58, v20, v21
	v_cvt_pk_bf16_f32 v59, v22, v23
	v_cvt_pk_bf16_f32 v60, v24, v25
	v_cvt_pk_bf16_f32 v61, v26, v27
	v_cvt_pk_bf16_f32 v62, v28, v29
	v_cvt_pk_bf16_f32 v63, v30, v31
	v_lshl_add_u64 v[68:69], v[118:119], 0, v[102:103]
	s_nop 1
	v_permlane32_swap_b32 v48, v50
	v_permlane32_swap_b32 v49, v51
	v_permlane32_swap_b32 v52, v54
	v_permlane32_swap_b32 v53, v55
	v_permlane32_swap_b32 v56, v58
	v_permlane32_swap_b32 v57, v59
	v_permlane32_swap_b32 v60, v62
	v_permlane32_swap_b32 v61, v63
	s_nop 1
	global_store_dwordx4 v[68:69], v[48:51], off
	global_store_dwordx4 v[68:69], v[52:55], off offset:32
	global_store_dwordx4 v[68:69], v[56:59], off offset:64
	global_store_dwordx4 v[68:69], v[60:63], off offset:96
	s_and_saveexec_b64 s[12:13], s[10:11]
	s_cbranch_execz .LBB0_1734
	v_lshlrev_b64 v[4:5], 7, v[116:117]
	v_lshl_add_u64 v[4:5], s[20:21], 0, v[4:5]
	global_store_dwordx2 v[4:5], v[2:3], off

.LBB0_1735:
	v_div_scale_f32 v0, s[12:13], v3, v3, 1.0
	v_rcp_f32_e32 v2, v0
	v_div_scale_f32 v4, vcc, 1.0, v3, 1.0
	v_fma_f32 v5, -v0, v2, 1.0
	v_fmac_f32_e32 v2, v5, v2
	v_mul_f32_e32 v5, v4, v2
	v_fma_f32 v6, -v0, v5, v4
	v_fmac_f32_e32 v5, v6, v2
	v_fma_f32 v0, -v0, v5, v4
	v_div_fmas_f32 v0, v0, v2, v5
	v_div_fixup_f32 v0, v0, v3, 1.0
	v_pk_mul_f32 v[66:67], v[32:33], v[0:1] op_sel_hi:[1,0]
	v_cvt_pk_bf16_f32 v48, v66, v67
	v_pk_mul_f32 v[66:67], v[34:35], v[0:1] op_sel_hi:[1,0]
	v_cvt_pk_bf16_f32 v49, v66, v67
	v_pk_mul_f32 v[66:67], v[36:37], v[0:1] op_sel_hi:[1,0]
	v_cvt_pk_bf16_f32 v50, v66, v67
	v_pk_mul_f32 v[66:67], v[38:39], v[0:1] op_sel_hi:[1,0]
	v_cvt_pk_bf16_f32 v51, v66, v67
	v_pk_mul_f32 v[66:67], v[40:41], v[0:1] op_sel_hi:[1,0]
	v_cvt_pk_bf16_f32 v52, v66, v67
	v_pk_mul_f32 v[66:67], v[42:43], v[0:1] op_sel_hi:[1,0]
	v_cvt_pk_bf16_f32 v53, v66, v67
	v_pk_mul_f32 v[66:67], v[44:45], v[0:1] op_sel_hi:[1,0]
	v_cvt_pk_bf16_f32 v54, v66, v67
	v_pk_mul_f32 v[66:67], v[46:47], v[0:1] op_sel_hi:[1,0]
	v_cvt_pk_bf16_f32 v55, v66, v67
	v_pk_mul_f32 v[66:67], v[16:17], v[0:1] op_sel_hi:[1,0]
	v_cvt_pk_bf16_f32 v56, v66, v67
	v_pk_mul_f32 v[66:67], v[18:19], v[0:1] op_sel_hi:[1,0]
	v_cvt_pk_bf16_f32 v57, v66, v67
	v_pk_mul_f32 v[66:67], v[20:21], v[0:1] op_sel_hi:[1,0]
	v_cvt_pk_bf16_f32 v58, v66, v67
	v_pk_mul_f32 v[66:67], v[22:23], v[0:1] op_sel_hi:[1,0]
	v_cvt_pk_bf16_f32 v59, v66, v67
	v_pk_mul_f32 v[66:67], v[24:25], v[0:1] op_sel_hi:[1,0]
	v_cvt_pk_bf16_f32 v60, v66, v67
	v_pk_mul_f32 v[66:67], v[26:27], v[0:1] op_sel_hi:[1,0]
	v_cvt_pk_bf16_f32 v61, v66, v67
	v_pk_mul_f32 v[66:67], v[28:29], v[0:1] op_sel_hi:[1,0]
	v_cvt_pk_bf16_f32 v62, v66, v67
	v_pk_mul_f32 v[66:67], v[30:31], v[0:1] op_sel_hi:[1,0]
	v_cvt_pk_bf16_f32 v63, v66, v67
	v_lshl_add_u64 v[68:69], v[112:113], 0, v[114:115]
	v_lshl_add_u64 v[68:69], v[68:69], 0, v[102:103]
	v_permlane32_swap_b32 v48, v50
	v_permlane32_swap_b32 v49, v51
	v_permlane32_swap_b32 v52, v54
	v_permlane32_swap_b32 v53, v55
	v_permlane32_swap_b32 v56, v58
	v_permlane32_swap_b32 v57, v59
	v_permlane32_swap_b32 v60, v62
	v_permlane32_swap_b32 v61, v63
	s_nop 1
	global_store_dwordx4 v[68:69], v[48:51], off
	global_store_dwordx4 v[68:69], v[52:55], off offset:32
	global_store_dwordx4 v[68:69], v[56:59], off offset:64
	global_store_dwordx4 v[68:69], v[60:63], off offset:96
	s_branch .LBB0_1685

.LBB0_3787:
	s_lshr_b32 s12, s40, 2
	s_and_b64 s[10:11], s[24:25], exec
	s_cselect_b32 s12, s12, s40
	s_and_b64 s[10:11], s[26:27], exec
	s_cselect_b32 s14, 0, s12
	s_and_b32 s10, s40, 3
	s_add_i32 s12, s40, s38
	s_or_b32 s13, s10, s37
	s_and_b64 s[10:11], s[24:25], exec
	s_cselect_b32 s13, s13, s36
	s_and_b64 s[10:11], s[26:27], exec
	s_cselect_b32 s13, s12, s13
	s_lshl_b32 s12, s13, 8
	s_add_i32 s42, s12, s29
	v_or_b32_e32 v120, s42, v122
	v_ashrrev_i32_e32 v121, 31, v120
	v_lshlrev_b64 v[2:3], s41, v[120:121]
	v_lshl_add_u64 v[116:117], v[2:3], 0, s[14:15]
	s_barrier
	v_lshlrev_b64 v[114:115], 11, v[116:117]
	v_lshl_add_u64 v[118:119], v[110:111], 0, v[114:115]
	s_cmp_eq_u32 s40, 0
	s_cbranch_scc1 .Lw0_L3
	s_and_b64 vcc, exec, s[22:23]
	s_cbranch_vccnz .Lw9_L3
	s_waitcnt vmcnt(4)
	s_branch .Lwd_L3

.LBB0_3833:
	v_cvt_pk_bf16_f32 v48, v32, v33
	v_cvt_pk_bf16_f32 v49, v34, v35
	v_cvt_pk_bf16_f32 v50, v36, v37
	v_cvt_pk_bf16_f32 v51, v38, v39
	v_cvt_pk_bf16_f32 v52, v40, v41
	v_cvt_pk_bf16_f32 v53, v42, v43
	v_cvt_pk_bf16_f32 v54, v44, v45
	v_cvt_pk_bf16_f32 v55, v46, v47
	s_nop 3
	v_cvt_pk_bf16_f32 v56, v16, v17
	v_cvt_pk_bf16_f32 v57, v18, v19
	v_cvt_pk_bf16_f32 v58, v20, v21
	v_cvt_pk_bf16_f32 v59, v22, v23
	v_cvt_pk_bf16_f32 v60, v24, v25
	v_cvt_pk_bf16_f32 v61, v26, v27
	v_cvt_pk_bf16_f32 v62, v28, v29
	v_cvt_pk_bf16_f32 v63, v30, v31
	v_lshl_add_u64 v[68:69], v[118:119], 0, v[102:103]
	s_nop 1
	v_permlane32_swap_b32 v48, v50
	v_permlane32_swap_b32 v49, v51
	v_permlane32_swap_b32 v52, v54
	v_permlane32_swap_b32 v53, v55
	v_permlane32_swap_b32 v56, v58
	v_permlane32_swap_b32 v57, v59
	v_permlane32_swap_b32 v60, v62
	v_permlane32_swap_b32 v61, v63
	s_nop 1
	global_store_dwordx4 v[68:69], v[48:51], off
	global_store_dwordx4 v[68:69], v[52:55], off offset:32
	global_store_dwordx4 v[68:69], v[56:59], off offset:64
	global_store_dwordx4 v[68:69], v[60:63], off offset:96
	s_and_saveexec_b64 s[10:11], s[8:9]
	s_cbranch_execz .LBB0_3835
	v_lshlrev_b64 v[4:5], 7, v[116:117]
	v_lshl_add_u64 v[4:5], s[18:19], 0, v[4:5]
	global_store_dwordx2 v[4:5], v[2:3], off

.LBB0_3836:
	v_div_scale_f32 v0, s[10:11], v3, v3, 1.0
	v_rcp_f32_e32 v2, v0
	v_div_scale_f32 v4, vcc, 1.0, v3, 1.0
	v_fma_f32 v5, -v0, v2, 1.0
	v_fmac_f32_e32 v2, v5, v2
	v_mul_f32_e32 v5, v4, v2
	v_fma_f32 v6, -v0, v5, v4
	v_fmac_f32_e32 v5, v6, v2
	v_fma_f32 v0, -v0, v5, v4
	v_div_fmas_f32 v0, v0, v2, v5
	v_div_fixup_f32 v0, v0, v3, 1.0
	v_pk_mul_f32 v[66:67], v[32:33], v[0:1] op_sel_hi:[1,0]
	v_cvt_pk_bf16_f32 v48, v66, v67
	v_pk_mul_f32 v[66:67], v[34:35], v[0:1] op_sel_hi:[1,0]
	v_cvt_pk_bf16_f32 v49, v66, v67
	v_pk_mul_f32 v[66:67], v[36:37], v[0:1] op_sel_hi:[1,0]
	v_cvt_pk_bf16_f32 v50, v66, v67
	v_pk_mul_f32 v[66:67], v[38:39], v[0:1] op_sel_hi:[1,0]
	v_cvt_pk_bf16_f32 v51, v66, v67
	v_pk_mul_f32 v[66:67], v[40:41], v[0:1] op_sel_hi:[1,0]
	v_cvt_pk_bf16_f32 v52, v66, v67
	v_pk_mul_f32 v[66:67], v[42:43], v[0:1] op_sel_hi:[1,0]
	v_cvt_pk_bf16_f32 v53, v66, v67
	v_pk_mul_f32 v[66:67], v[44:45], v[0:1] op_sel_hi:[1,0]
	v_cvt_pk_bf16_f32 v54, v66, v67
	v_pk_mul_f32 v[66:67], v[46:47], v[0:1] op_sel_hi:[1,0]
	v_cvt_pk_bf16_f32 v55, v66, v67
	v_pk_mul_f32 v[66:67], v[16:17], v[0:1] op_sel_hi:[1,0]
	v_cvt_pk_bf16_f32 v56, v66, v67
	v_pk_mul_f32 v[66:67], v[18:19], v[0:1] op_sel_hi:[1,0]
	v_cvt_pk_bf16_f32 v57, v66, v67
	v_pk_mul_f32 v[66:67], v[20:21], v[0:1] op_sel_hi:[1,0]
	v_cvt_pk_bf16_f32 v58, v66, v67
	v_pk_mul_f32 v[66:67], v[22:23], v[0:1] op_sel_hi:[1,0]
	v_cvt_pk_bf16_f32 v59, v66, v67
	v_pk_mul_f32 v[66:67], v[24:25], v[0:1] op_sel_hi:[1,0]
	v_cvt_pk_bf16_f32 v60, v66, v67
	v_pk_mul_f32 v[66:67], v[26:27], v[0:1] op_sel_hi:[1,0]
	v_cvt_pk_bf16_f32 v61, v66, v67
	v_pk_mul_f32 v[66:67], v[28:29], v[0:1] op_sel_hi:[1,0]
	v_cvt_pk_bf16_f32 v62, v66, v67
	v_pk_mul_f32 v[66:67], v[30:31], v[0:1] op_sel_hi:[1,0]
	v_cvt_pk_bf16_f32 v63, v66, v67
	v_lshl_add_u64 v[68:69], v[112:113], 0, v[114:115]
	v_lshl_add_u64 v[68:69], v[68:69], 0, v[102:103]
	v_permlane32_swap_b32 v48, v50
	v_permlane32_swap_b32 v49, v51
	v_permlane32_swap_b32 v52, v54
	v_permlane32_swap_b32 v53, v55
	v_permlane32_swap_b32 v56, v58
	v_permlane32_swap_b32 v57, v59
	v_permlane32_swap_b32 v60, v62
	v_permlane32_swap_b32 v61, v63
	s_nop 1
	global_store_dwordx4 v[68:69], v[48:51], off
	global_store_dwordx4 v[68:69], v[52:55], off offset:32
	global_store_dwordx4 v[68:69], v[56:59], off offset:64
	global_store_dwordx4 v[68:69], v[60:63], off offset:96
	s_branch .LBB0_3786
